# CONV GEMM (ph10): wave owns 64 contiguous tile columns (B-fragment LDS remap), WUP rows laid out 64g+32hi+r by the phase-0 transpose
# speedup vs baseline: 1.0070x; 1.0044x over previous
.LBB0_121:
	s_add_i32 m0, s3, 0x18000
	v_lshl_add_u64 v[10:11], v[10:11], 0, s[4:5]
	s_waitcnt vmcnt(2)
	s_barrier
	global_load_lds_dwordx4 v[10:11], off
	v_lshl_add_u64 v[6:7], v[6:7], 0, s[4:5]
	s_add_i32 m0, s3, 0x1a000
	s_add_i32 s80, s3, 0x8000
	global_load_lds_dwordx4 v[6:7], off
	v_lshl_add_u64 v[6:7], v[8:9], 0, s[4:5]
	s_mov_b32 m0, s80
	s_add_i32 s84, s3, 0xa000
	global_load_lds_dwordx4 v[6:7], off
	v_lshl_add_u64 v[6:7], v[12:13], 0, s[4:5]
	s_mov_b32 m0, s84
	v_lshl_add_u64 v[4:5], v[4:5], 0, s[4:5]
	global_load_lds_dwordx4 v[6:7], off
	s_add_i32 m0, s3, 0x1c000
	v_lshl_add_u64 v[2:3], v[2:3], 0, s[4:5]
	global_load_lds_dwordx4 v[4:5], off
	s_add_i32 m0, s3, 0x1e000
	s_lshl_b32 s11, s11, 5
	global_load_lds_dwordx4 v[2:3], off
	v_lshrrev_b32_e32 v2, 1, v15
	v_and_b32_e32 v2, 24, v2
	s_and_b32 s34, s11, 0x60
	v_and_b32_e32 v1, 15, v15
	v_lshlrev_b32_e32 v3, 1, v2
	v_or_b32_e32 v172, s34, v2
	v_rcp_iflag_f32_e32 v2, v14
	v_lshlrev_b32_e32 v241, 2, v1
	s_lshr_b32 s83, s10, 6
	v_lshl_or_b32 v3, v1, 6, v3
	v_and_b32_e32 v4, 32, v241
	s_mov_b32 s100, 0x14000
	s_mov_b32 s11, 7
	s_cmp_eq_u32 s81, 0
	s_cbranch_scc1 .Lfl_remap
	s_cmp_eq_u32 s81, 3
	s_cbranch_scc1 .Lfl_remap
	s_cmp_eq_u32 s81, 4
	s_cbranch_scc1 .Lfl_remap
	s_branch .Lfl_noremap

.LBB0_465:
	s_andn2_saveexec_b64 s[22:23], s[22:23]
	s_cbranch_execz .LBB0_467
	v_add_u16_e32 v20, 0xf280, v1
	v_mul_u32_u24_e32 v21, 0xba2f, v20
	s_load_dwordx2 s[26:27], s[0:1], 0xe8
	v_lshrrev_b32_e32 v21, 23, v21
	v_mul_lo_u16_e32 v22, 0xb0, v21
	v_sub_u16_e32 v31, v20, v22
	v_lshlrev_b16_e32 v50, 5, v31
	v_lshlrev_b16_e32 v32, 6, v21
	v_lshlrev_b32_e32 v20, 2, v50
	v_mov_b32_e32 v21, v0
	v_or_b32_e32 v33, v3, v32
	s_waitcnt lgkmcnt(0)
	v_lshl_add_u64 v[20:21], s[26:27], 0, v[20:21]
	v_lshlrev_b32_e32 v22, 2, v4
	v_mov_b32_e32 v23, v0
	v_lshl_add_u64 v[20:21], v[20:21], 0, v[22:23]
	v_mul_u32_u24_e32 v22, 0x1600, v33
	v_lshlrev_b32_e32 v22, 2, v22
	v_lshl_add_u64 v[20:21], v[20:21], 0, v[22:23]
	v_add_co_u32_e32 v22, vcc, s28, v20
	global_load_dword v33, v[20:21], off
	s_nop 0
	v_addc_co_u32_e32 v23, vcc, 0, v21, vcc
	global_load_dword v34, v[22:23], off
	v_add_co_u32_e32 v22, vcc, s55, v20
	s_mov_b32 s25, 0x21000
	s_nop 0
	v_addc_co_u32_e32 v23, vcc, 0, v21, vcc
	global_load_dword v35, v[22:23], off
	v_add_co_u32_e32 v22, vcc, s25, v20
	s_mov_b32 s25, 0x37000
	s_nop 0
	v_addc_co_u32_e32 v23, vcc, 0, v21, vcc
	global_load_dword v36, v[22:23], off
	v_add_co_u32_e32 v22, vcc, s49, v20
	s_nop 1
	v_addc_co_u32_e32 v23, vcc, 0, v21, vcc
	global_load_dword v37, v[22:23], off
	v_add_co_u32_e32 v22, vcc, s25, v20
	s_mov_b32 s25, 0x42000
	s_nop 0
	v_addc_co_u32_e32 v23, vcc, 0, v21, vcc
	global_load_dword v38, v[22:23], off
	v_add_co_u32_e32 v22, vcc, s25, v20
	s_mov_b32 s25, 0x4d000
	s_nop 0
	v_addc_co_u32_e32 v23, vcc, 0, v21, vcc
	global_load_dword v39, v[22:23], off
	v_add_co_u32_e32 v22, vcc, s25, v20
	s_mov_b32 s25, 0x58000
	s_nop 0
	v_addc_co_u32_e32 v23, vcc, 0, v21, vcc
	global_load_dword v40, v[22:23], off
	v_add_co_u32_e32 v22, vcc, s25, v20
	s_mov_b32 s25, 0x63000
	s_nop 0
	v_addc_co_u32_e32 v23, vcc, 0, v21, vcc
	global_load_dword v41, v[22:23], off
	v_add_co_u32_e32 v22, vcc, s25, v20
	s_mov_b32 s25, 0x6e000
	s_nop 0
	v_addc_co_u32_e32 v23, vcc, 0, v21, vcc
	global_load_dword v42, v[22:23], off
	v_add_co_u32_e32 v22, vcc, s25, v20
	s_mov_b32 s25, 0x79000
	s_nop 0
	v_addc_co_u32_e32 v23, vcc, 0, v21, vcc
	global_load_dword v43, v[22:23], off
	v_add_co_u32_e32 v22, vcc, s25, v20
	s_mov_b32 s25, 0x84000
	s_nop 0
	v_addc_co_u32_e32 v23, vcc, 0, v21, vcc
	global_load_dword v44, v[22:23], off
	v_add_co_u32_e32 v22, vcc, s25, v20
	s_mov_b32 s25, 0x8f000
	s_nop 0
	v_addc_co_u32_e32 v23, vcc, 0, v21, vcc
	global_load_dword v45, v[22:23], off
	v_add_co_u32_e32 v22, vcc, s25, v20
	s_mov_b32 s25, 0x9a000
	s_nop 0
	v_addc_co_u32_e32 v23, vcc, 0, v21, vcc
	global_load_dword v46, v[22:23], off
	v_add_co_u32_e32 v22, vcc, s25, v20
	s_mov_b32 s25, 0xa5000
	s_nop 0
	v_addc_co_u32_e32 v23, vcc, 0, v21, vcc
	global_load_dword v47, v[22:23], off
	v_add_co_u32_e32 v22, vcc, s25, v20
	s_mov_b32 s25, 0xb0000
	s_nop 0
	v_addc_co_u32_e32 v23, vcc, 0, v21, vcc
	global_load_dword v48, v[22:23], off
	v_add_co_u32_e32 v22, vcc, s25, v20
	s_mov_b32 s25, 0xbb000
	s_nop 0
	v_addc_co_u32_e32 v23, vcc, 0, v21, vcc
	global_load_dword v49, v[22:23], off
	v_add_co_u32_e32 v22, vcc, s25, v20
	s_mov_b32 s25, 0xc6000
	s_nop 0
	v_addc_co_u32_e32 v23, vcc, 0, v21, vcc
	global_load_dword v51, v[22:23], off
	v_add_co_u32_e32 v22, vcc, s25, v20
	s_mov_b32 s25, 0xd1000
	s_nop 0
	v_addc_co_u32_e32 v23, vcc, 0, v21, vcc
	global_load_dword v52, v[22:23], off
	v_add_co_u32_e32 v22, vcc, s25, v20
	s_mov_b32 s25, 0xdc000
	s_nop 0
	v_addc_co_u32_e32 v23, vcc, 0, v21, vcc
	global_load_dword v53, v[22:23], off
	v_add_co_u32_e32 v22, vcc, s25, v20
	s_mov_b32 s25, 0xe7000
	s_nop 0
	v_addc_co_u32_e32 v23, vcc, 0, v21, vcc
	global_load_dword v54, v[22:23], off
	v_add_co_u32_e32 v22, vcc, s25, v20
	s_mov_b32 s25, 0xf2000
	s_nop 0
	v_addc_co_u32_e32 v23, vcc, 0, v21, vcc
	global_load_dword v55, v[22:23], off
	v_add_co_u32_e32 v22, vcc, s25, v20
	s_mov_b32 s25, 0xfd000
	s_nop 0
	v_addc_co_u32_e32 v23, vcc, 0, v21, vcc
	global_load_dword v56, v[22:23], off
	v_add_co_u32_e32 v22, vcc, s25, v20
	s_mov_b32 s25, 0x108000
	s_nop 0
	v_addc_co_u32_e32 v23, vcc, 0, v21, vcc
	global_load_dword v57, v[22:23], off
	v_add_co_u32_e32 v22, vcc, s25, v20
	s_mov_b32 s25, 0x113000
	s_nop 0
	v_addc_co_u32_e32 v23, vcc, 0, v21, vcc
	global_load_dword v58, v[22:23], off
	v_add_co_u32_e32 v22, vcc, s25, v20
	s_mov_b32 s25, 0x11e000
	s_nop 0
	v_addc_co_u32_e32 v23, vcc, 0, v21, vcc
	global_load_dword v59, v[22:23], off
	v_add_co_u32_e32 v22, vcc, s25, v20
	s_mov_b32 s25, 0x129000
	s_nop 0
	v_addc_co_u32_e32 v23, vcc, 0, v21, vcc
	global_load_dword v60, v[22:23], off
	v_add_co_u32_e32 v22, vcc, s25, v20
	s_mov_b32 s25, 0x134000
	s_nop 0
	v_addc_co_u32_e32 v23, vcc, 0, v21, vcc
	global_load_dword v61, v[22:23], off
	v_add_co_u32_e32 v22, vcc, s25, v20
	s_mov_b32 s25, 0x13f000
	s_nop 0
	v_addc_co_u32_e32 v23, vcc, 0, v21, vcc
	global_load_dword v62, v[22:23], off
	v_add_co_u32_e32 v22, vcc, s25, v20
	s_mov_b32 s25, 0x14a000
	s_nop 0
	v_addc_co_u32_e32 v23, vcc, 0, v21, vcc
	global_load_dword v63, v[22:23], off
	v_add_co_u32_e32 v22, vcc, s25, v20
	s_mov_b32 s25, 0x155000
	s_nop 0
	v_addc_co_u32_e32 v23, vcc, 0, v21, vcc
	v_add_co_u32_e32 v20, vcc, s25, v20
	global_load_dword v22, v[22:23], off
	s_nop 0
	v_addc_co_u32_e32 v21, vcc, 0, v21, vcc
	global_load_dword v20, v[20:21], off
	v_add_u32_e32 v21, 0x400, v5
	s_waitcnt vmcnt(30)
	ds_write2_b32 v5, v33, v34 offset1:66
	s_waitcnt vmcnt(28)
	ds_write2_b32 v5, v35, v36 offset0:132 offset1:198
	s_waitcnt vmcnt(26)
	ds_write2_b32 v21, v37, v38 offset0:8 offset1:74
	s_waitcnt vmcnt(24)
	ds_write2_b32 v21, v39, v40 offset0:140 offset1:206
	v_add_u32_e32 v21, 0x800, v5
	s_waitcnt vmcnt(22)
	ds_write2_b32 v21, v41, v42 offset0:16 offset1:82
	s_waitcnt vmcnt(20)
	ds_write2_b32 v21, v43, v44 offset0:148 offset1:214
	v_add_u32_e32 v21, 0xc00, v5
	s_waitcnt vmcnt(18)
	ds_write2_b32 v21, v45, v46 offset0:24 offset1:90
	s_waitcnt vmcnt(16)
	ds_write2_b32 v21, v47, v48 offset0:156 offset1:222
	v_add_u32_e32 v21, 0x1000, v5
	s_waitcnt vmcnt(14)
	ds_write2_b32 v21, v49, v51 offset0:32 offset1:98
	s_waitcnt vmcnt(12)
	ds_write2_b32 v21, v52, v53 offset0:164 offset1:230
	v_add_u32_e32 v21, 0x1400, v5
	s_waitcnt vmcnt(10)
	ds_write2_b32 v21, v54, v55 offset0:40 offset1:106
	s_waitcnt vmcnt(8)
	ds_write2_b32 v21, v56, v57 offset0:172 offset1:238
	v_add_u32_e32 v21, 0x1800, v5
	s_waitcnt vmcnt(6)
	ds_write2_b32 v21, v58, v59 offset0:48 offset1:114
	s_waitcnt vmcnt(4)
	ds_write2_b32 v21, v60, v61 offset0:180 offset1:246
	v_add_u32_e32 v21, 0x1c00, v5
	s_waitcnt vmcnt(2)
	ds_write2_b32 v21, v62, v63 offset0:56 offset1:122
	s_waitcnt vmcnt(0)
	ds_write2_b32 v21, v22, v20 offset0:188 offset1:254
	s_movk_i32 s25, 0x58
	s_waitcnt lgkmcnt(0)
	v_cmp_gt_u16_e32 vcc, s25, v31
	v_mov_b32_e32 v31, 0xfffff500
	v_lshlrev_b32_e32 v20, 1, v32
	v_mov_b32_e32 v21, v0
	ds_read2_b32 v[32:33], v24 offset0:33 offset1:41
	ds_read2_b32 v[34:35], v24 offset1:8
	ds_read2_b32 v[36:37], v24 offset0:66 offset1:74
	ds_read2_b32 v[38:39], v24 offset0:99 offset1:107
	ds_read2_b32 v[40:41], v24 offset0:132 offset1:140
	ds_read2_b32 v[42:43], v24 offset0:165 offset1:173
	ds_read2_b32 v[44:45], v24 offset0:198 offset1:206
	ds_read2_b32 v[46:47], v24 offset0:231 offset1:239
	v_cndmask_b32_e64 v31, v31, 0, vcc
	v_lshl_add_u64 v[48:49], v[8:9], 0, v[20:21]
	s_waitcnt lgkmcnt(6)
	v_cvt_pk_bf16_f32 v20, v34, v32
	v_add_lshl_u32 v31, v31, v50, 1
	v_mov_b32_e32 v32, 0x20
	v_and_b32_e32 v31, 0xffffff00, v31
	v_cndmask_b32_e64 v32, v32, 0, vcc
	v_and_b32_e32 v34, 0x60, v50
	v_lshlrev_b32_e32 v34, 1, v34
	v_or3_b32 v31, v34, v32, v31
	v_or_b32_e32 v50, v31, v19
	v_ashrrev_i32_e32 v51, 31, v50
	v_lshlrev_b64 v[50:51], 11, v[50:51]
	v_lshl_add_u64 v[50:51], v[48:49], 0, v[50:51]
	v_or_b32_e32 v32, v31, v25
	s_waitcnt lgkmcnt(4)
	v_cvt_pk_bf16_f32 v21, v36, v38
	s_waitcnt lgkmcnt(2)
	v_cvt_pk_bf16_f32 v22, v40, v42
	s_waitcnt lgkmcnt(0)
	v_cvt_pk_bf16_f32 v23, v44, v46
	global_store_dwordx4 v[50:51], v[20:23], off
	s_nop 1
	v_cvt_pk_bf16_f32 v20, v35, v33
	v_ashrrev_i32_e32 v33, 31, v32
	v_lshlrev_b64 v[32:33], 11, v[32:33]
	v_cvt_pk_bf16_f32 v21, v37, v39
	v_cvt_pk_bf16_f32 v22, v41, v43
	v_cvt_pk_bf16_f32 v23, v45, v47
	v_lshl_add_u64 v[32:33], v[48:49], 0, v[32:33]
	ds_read2_b32 v[34:35], v24 offset0:16 offset1:24
	ds_read2_b32 v[36:37], v24 offset0:49 offset1:57
	ds_read2_b32 v[38:39], v24 offset0:82 offset1:90
	ds_read2_b32 v[40:41], v24 offset0:115 offset1:123
	ds_read2_b32 v[42:43], v24 offset0:148 offset1:156
	ds_read2_b32 v[44:45], v24 offset0:181 offset1:189
	ds_read2_b32 v[46:47], v24 offset0:214 offset1:222
	ds_read2_b32 v[50:51], v24 offset0:247 offset1:255
	global_store_dwordx4 v[32:33], v[20:23], off
	v_or_b32_e32 v32, v31, v26
	v_ashrrev_i32_e32 v33, 31, v32
	v_lshlrev_b64 v[32:33], 11, v[32:33]
	v_lshl_add_u64 v[32:33], v[48:49], 0, v[32:33]
	s_waitcnt lgkmcnt(6)
	v_cvt_pk_bf16_f32 v20, v34, v36
	s_waitcnt lgkmcnt(4)
	v_cvt_pk_bf16_f32 v21, v38, v40
	s_waitcnt lgkmcnt(2)
	v_cvt_pk_bf16_f32 v22, v42, v44
	s_waitcnt lgkmcnt(0)
	v_cvt_pk_bf16_f32 v23, v46, v50
	global_store_dwordx4 v[32:33], v[20:23], off
	v_or_b32_e32 v32, v31, v27
	v_ashrrev_i32_e32 v33, 31, v32
	v_lshlrev_b64 v[32:33], 11, v[32:33]
	v_lshl_add_u64 v[32:33], v[48:49], 0, v[32:33]
	v_cvt_pk_bf16_f32 v20, v35, v37
	v_cvt_pk_bf16_f32 v21, v39, v41
	v_cvt_pk_bf16_f32 v22, v43, v45
	v_cvt_pk_bf16_f32 v23, v47, v51
	global_store_dwordx4 v[32:33], v[20:23], off
	s_waitcnt lgkmcnt(0)
